# barrier v3: L1 invalidate issued before the wait + two polls in flight (on v11 stack)
# speedup vs baseline: 1.0097x; 1.0097x over previous
; __device__ __forceinline__ unsigned xb_ld(unsigned* p)              { return __hip_atomic_load(p, __ATOMIC_RELAXED, __HIP_MEMORY_SCOPE_AGENT); }
; __device__ __forceinline__ unsigned xb_add(unsigned* p, unsigned v) { return __hip_atomic_fetch_add(p, v, __ATOMIC_RELAXED, __HIP_MEMORY_SCOPE_AGENT); }
; #define XB_SPIN(cond, bar) do { unsigned _sp = 0; while (cond) { __builtin_amdgcn_s_sleep(1); \
;     if ((++_sp & 255u) == 0u) { if (xb_ld(&(bar)[XB_TMO])) break; if (_sp > XB_SPIN_CAP) { atomicAdd(&(bar)[XB_TMO], 1u); break; } } } } while (0)
; __device__ __forceinline__ void xcd_barrier(const XcdBarrier& b) {
;     asm volatile("s_waitcnt vmcnt(0)" ::: "memory");
;     __syncthreads();
;     if (threadIdx.x == 0) {
;         unsigned* bar = b.bar;
;         __builtin_amdgcn_s_waitcnt(0);
;         unsigned nloc = b.st[0], nx = b.st[1];
;         if (nloc == 0u) { xcd_barrier_complete(bar, b.x, nloc, nx); b.st[0] = nloc; b.st[1] = nx; }
;         const unsigned old = xb_add(&bar[XB_XSUB(b.x)], 1u);
;         const unsigned gen = old / nloc;
;         if (old + 1u == (gen + 1u) * nloc) {
;             __builtin_amdgcn_fence(__ATOMIC_RELEASE, "agent");
;             asm volatile("s_waitcnt vmcnt(0)" ::: "memory");
;             const unsigned og = xb_add(&bar[XB_TOP], 1u);
;             const unsigned tg = og / nx;
;             if (og + 1u == (tg + 1u) * nx) xb_add(&bar[XB_TOPGEN], 1u);
;             else XB_SPIN(xb_ld(&bar[XB_TOPGEN]) == tg, bar);
;             __builtin_amdgcn_fence(__ATOMIC_ACQUIRE, "agent");
;             xb_add(&bar[XB_XGEN(b.x)], 1u);
;             asm volatile("s_waitcnt vmcnt(0)" ::: "memory");
;         } else {
;             XB_SPIN(xb_ld(&bar[XB_XGEN(b.x)]) == gen, bar);
;             __builtin_amdgcn_fence(__ATOMIC_ACQUIRE, "agent");
;             asm volatile("s_waitcnt vmcnt(0)" ::: "memory");
;         }
;     }
;     __syncthreads();
; }
.LBB0_601:
	v_readlane_b32 s2, v254, 50
	v_readlane_b32 s3, v254, 51
	v_mov_b32_e32 v3, 1
	s_add_i32 s101, s101, 1
	s_waitcnt lgkmcnt(0)
	buffer_inv sc1
	s_nop 4
	global_atomic_add v5, v99, v3, s[2:3] sc0
	v_readfirstlane_b32 s6, v4
	v_readfirstlane_b32 s7, v2
	s_mul_i32 s6, s6, s101
	s_mul_i32 s7, s7, s101
	s_add_u32 s8, s62, 0x2400
	s_addc_u32 s9, s63, 0
	v_readlane_b32 s2, v254, 52
	v_readlane_b32 s3, v254, 53
	s_mov_b32 s10, 0
	s_waitcnt vmcnt(0)
	v_readfirstlane_b32 s11, v5
	s_add_i32 s11, s11, 1
	s_cmp_lg_u32 s11, s6
	s_cbranch_scc1 .Lmy_bar_spin
	global_atomic_add v99, v3, s[8:9]
	global_atomic_add v99, v3, s[8:9] offset:256
	global_atomic_add v99, v3, s[8:9] offset:512
	global_atomic_add v99, v3, s[8:9] offset:768
	global_atomic_add v99, v3, s[8:9] offset:1024
	global_atomic_add v99, v3, s[8:9] offset:1280
	global_atomic_add v99, v3, s[8:9] offset:1536
	global_atomic_add v99, v3, s[8:9] offset:1792
	global_atomic_add v99, v3, s[8:9] offset:2048
	global_atomic_add v99, v3, s[8:9] offset:2304
	global_atomic_add v99, v3, s[8:9] offset:2560
	global_atomic_add v99, v3, s[8:9] offset:2816
	global_atomic_add v99, v3, s[8:9] offset:3072
	global_atomic_add v99, v3, s[8:9] offset:3328
	global_atomic_add v99, v3, s[8:9] offset:3584
	global_atomic_add v99, v3, s[8:9] offset:3840
.Lmy_bar_spin:
	global_load_dword v5, v99, s[2:3] sc1
	s_sleep 5
	global_load_dword v6, v99, s[2:3] sc1
.Lmy_bar_loop:
	s_waitcnt vmcnt(1)
	v_readfirstlane_b32 s11, v5
	s_cmp_ge_u32 s11, s7
	s_cbranch_scc1 .Lmy_bar_done
	global_load_dword v5, v99, s[2:3] sc1
	s_waitcnt vmcnt(1)
	v_readfirstlane_b32 s11, v6
	s_cmp_ge_u32 s11, s7
	s_cbranch_scc1 .Lmy_bar_done
	global_load_dword v6, v99, s[2:3] sc1
	s_add_i32 s10, s10, 1
	s_cmp_lt_u32 s10, 0x10000
	s_cbranch_scc1 .Lmy_bar_loop
.Lmy_bar_done:
	s_waitcnt vmcnt(0)
.LBB0_633:
	s_or_b64 exec, exec, s[0:1]
	s_waitcnt lgkmcnt(0)
	s_barrier
